# attention: the staged next K/V tile is written to LDS after the last PV MFMA of the iteration instead of between the tail MFMAs
# speedup vs baseline: 1.0149x; 1.0048x over previous
.Lat_nr1:
	v_exp_f32_e32 v64, v64
	v_exp_f32_e32 v65, v65
	v_exp_f32_e32 v66, v66
	v_exp_f32_e32 v67, v67
	v_add_f32_e32 v202, v202, v64
	v_exp_f32_e32 v68, v68
	v_exp_f32_e32 v69, v69
	v_add_f32_e32 v202, v202, v66
	v_exp_f32_e32 v70, v70
	v_add_f32_e32 v214, v65, v67
	v_cvt_pk_bf16_f32 v64, v64, v65
	v_exp_f32_e32 v71, v71
	v_add_f32_e32 v202, v202, v68
	v_exp_f32_e32 v72, v72
	v_add_f32_e32 v214, v214, v69
	v_cvt_pk_bf16_f32 v65, v66, v67
	v_exp_f32_e32 v73, v73
	v_add_f32_e32 v202, v202, v70
	v_exp_f32_e32 v74, v74
	v_add_f32_e32 v214, v214, v71
	v_cvt_pk_bf16_f32 v66, v68, v69
	v_exp_f32_e32 v75, v75
	v_add_f32_e32 v202, v202, v72
	v_exp_f32_e32 v76, v76
	v_add_f32_e32 v214, v214, v73
	v_cvt_pk_bf16_f32 v67, v70, v71
	v_exp_f32_e32 v77, v77
	v_add_f32_e32 v202, v202, v74
	s_waitcnt lgkmcnt(3)
	v_mfma_f32_32x32x16_bf16 v[16:31], v[236:239], v[64:67], v[16:31]
	v_exp_f32_e32 v78, v78
	v_add_f32_e32 v214, v214, v75
	v_cvt_pk_bf16_f32 v68, v72, v73
	v_exp_f32_e32 v79, v79
	v_add_f32_e32 v202, v202, v76
	v_exp_f32_e32 v80, v80
	v_add_f32_e32 v214, v214, v77
	v_cvt_pk_bf16_f32 v69, v74, v75
	s_waitcnt lgkmcnt(2)
	v_mfma_f32_32x32x16_bf16 v[0:15], v[240:243], v[64:67], v[0:15]
	v_exp_f32_e32 v81, v81
	v_add_f32_e32 v202, v202, v78
	v_exp_f32_e32 v82, v82
	v_add_f32_e32 v214, v214, v79
	v_cvt_pk_bf16_f32 v70, v76, v77
	v_exp_f32_e32 v83, v83
	v_add_f32_e32 v202, v202, v80
	v_exp_f32_e32 v84, v84
	v_add_f32_e32 v214, v214, v81
	v_cvt_pk_bf16_f32 v71, v78, v79
	v_exp_f32_e32 v85, v85
	v_add_f32_e32 v202, v202, v82
	s_waitcnt lgkmcnt(1)
	v_mfma_f32_32x32x16_bf16 v[16:31], v[244:247], v[68:71], v[16:31]
	v_exp_f32_e32 v86, v86
	v_add_f32_e32 v214, v214, v83
	v_cvt_pk_bf16_f32 v72, v80, v81
	v_exp_f32_e32 v87, v87
	v_add_f32_e32 v202, v202, v84
	v_exp_f32_e32 v88, v88
	v_add_f32_e32 v214, v214, v85
	v_cvt_pk_bf16_f32 v73, v82, v83
	s_waitcnt lgkmcnt(0)
	v_mfma_f32_32x32x16_bf16 v[0:15], v[248:251], v[68:71], v[0:15]
	v_exp_f32_e32 v89, v89
	v_add_f32_e32 v202, v202, v86
	v_exp_f32_e32 v90, v90
	v_add_f32_e32 v214, v214, v87
	v_cvt_pk_bf16_f32 v74, v84, v85
	v_exp_f32_e32 v91, v91
	v_add_f32_e32 v202, v202, v88
	v_exp_f32_e32 v92, v92
	v_add_f32_e32 v214, v214, v89
	v_cvt_pk_bf16_f32 v75, v86, v87
	v_exp_f32_e32 v93, v93
	v_add_f32_e32 v202, v202, v90
	v_exp_f32_e32 v94, v94
	v_add_f32_e32 v214, v214, v91
	v_cvt_pk_bf16_f32 v76, v88, v89
	v_exp_f32_e32 v95, v95
	v_add_f32_e32 v202, v202, v92
	v_add_f32_e32 v214, v214, v93
	v_cvt_pk_bf16_f32 v77, v90, v91
	v_add_f32_e32 v202, v202, v94
	v_add_f32_e32 v214, v214, v95
	v_cvt_pk_bf16_f32 v78, v92, v93
	v_cvt_pk_bf16_f32 v79, v94, v95
	v_add_f32_e32 v202, v202, v214
	ds_read_b128 v[80:83], v218 offset:13376
	ds_read_b128 v[84:87], v218 offset:17984
	ds_read_b128 v[88:91], v218 offset:13408
	ds_read_b128 v[92:95], v218 offset:18016
	v_exp_f32_e32 v96, v96
	v_exp_f32_e32 v97, v97
	v_exp_f32_e32 v98, v98
	v_exp_f32_e32 v99, v99
	v_add_f32_e32 v203, v203, v96
	v_exp_f32_e32 v100, v100
	v_exp_f32_e32 v101, v101
	v_add_f32_e32 v203, v203, v98
	v_exp_f32_e32 v102, v102
	v_add_f32_e32 v216, v97, v99
	v_cvt_pk_bf16_f32 v96, v96, v97
	v_exp_f32_e32 v103, v103
	v_add_f32_e32 v203, v203, v100
	v_exp_f32_e32 v104, v104
	s_waitcnt lgkmcnt(3)
	v_mfma_f32_32x32x16_bf16 v[16:31], v[80:83], v[72:75], v[16:31]
	v_add_f32_e32 v216, v216, v101
	v_cvt_pk_bf16_f32 v97, v98, v99
	v_exp_f32_e32 v105, v105
	v_add_f32_e32 v203, v203, v102
	v_exp_f32_e32 v106, v106
	v_add_f32_e32 v216, v216, v103
	v_cvt_pk_bf16_f32 v98, v100, v101
	v_exp_f32_e32 v107, v107
	s_waitcnt lgkmcnt(2)
	v_mfma_f32_32x32x16_bf16 v[0:15], v[84:87], v[72:75], v[0:15]
	v_add_f32_e32 v203, v203, v104
	v_exp_f32_e32 v108, v108
	v_add_f32_e32 v216, v216, v105
	v_cvt_pk_bf16_f32 v99, v102, v103
	v_exp_f32_e32 v109, v109
	v_add_f32_e32 v203, v203, v106
	v_exp_f32_e32 v110, v110
	v_add_f32_e32 v216, v216, v107
	s_waitcnt lgkmcnt(1)
	v_mfma_f32_32x32x16_bf16 v[16:31], v[88:91], v[76:79], v[16:31]
	v_cvt_pk_bf16_f32 v100, v104, v105
	v_exp_f32_e32 v111, v111
	v_add_f32_e32 v203, v203, v108
	v_exp_f32_e32 v112, v112
	v_add_f32_e32 v216, v216, v109
	v_cvt_pk_bf16_f32 v101, v106, v107
	v_exp_f32_e32 v113, v113
	v_add_f32_e32 v203, v203, v110
	s_waitcnt lgkmcnt(0)
	v_mfma_f32_32x32x16_bf16 v[0:15], v[92:95], v[76:79], v[0:15]
	v_exp_f32_e32 v114, v114
	v_add_f32_e32 v216, v216, v111
	v_cvt_pk_bf16_f32 v102, v108, v109
	v_exp_f32_e32 v115, v115
	v_add_f32_e32 v203, v203, v112
	v_exp_f32_e32 v116, v116
	v_add_f32_e32 v216, v216, v113
	v_cvt_pk_bf16_f32 v103, v110, v111
	v_mfma_f32_32x32x16_bf16 v[48:63], v[236:239], v[96:99], v[48:63]
	v_exp_f32_e32 v117, v117
	v_add_f32_e32 v203, v203, v114
	v_exp_f32_e32 v118, v118
	v_add_f32_e32 v216, v216, v115
	v_cvt_pk_bf16_f32 v104, v112, v113
	v_exp_f32_e32 v119, v119
	v_add_f32_e32 v203, v203, v116
	v_exp_f32_e32 v120, v120
	v_mfma_f32_32x32x16_bf16 v[32:47], v[240:243], v[96:99], v[32:47]
	v_add_f32_e32 v216, v216, v117
	v_cvt_pk_bf16_f32 v105, v114, v115
	v_exp_f32_e32 v121, v121
	v_add_f32_e32 v203, v203, v118
	v_exp_f32_e32 v122, v122
	v_add_f32_e32 v216, v216, v119
	v_cvt_pk_bf16_f32 v106, v116, v117
	v_exp_f32_e32 v123, v123
	v_mfma_f32_32x32x16_bf16 v[48:63], v[244:247], v[100:103], v[48:63]
	v_add_f32_e32 v203, v203, v120
	v_exp_f32_e32 v124, v124
	v_add_f32_e32 v216, v216, v121
	v_cvt_pk_bf16_f32 v107, v118, v119
	v_exp_f32_e32 v125, v125
	v_add_f32_e32 v203, v203, v122
	v_exp_f32_e32 v126, v126
	v_add_f32_e32 v216, v216, v123
	v_mfma_f32_32x32x16_bf16 v[32:47], v[248:251], v[100:103], v[32:47]
	v_cvt_pk_bf16_f32 v108, v120, v121
	v_exp_f32_e32 v127, v127
	v_add_f32_e32 v203, v203, v124
	v_add_f32_e32 v216, v216, v125
	v_cvt_pk_bf16_f32 v109, v122, v123
	v_add_f32_e32 v203, v203, v126
	v_add_f32_e32 v216, v216, v127
	v_cvt_pk_bf16_f32 v110, v124, v125
	v_cvt_pk_bf16_f32 v111, v126, v127
	v_add_f32_e32 v203, v203, v216
	s_nop 0
	v_mfma_f32_32x32x16_bf16 v[48:63], v[80:83], v[104:107], v[48:63]
	v_mfma_f32_32x32x16_bf16 v[32:47], v[84:87], v[104:107], v[32:47]
	v_mfma_f32_32x32x16_bf16 v[48:63], v[88:91], v[108:111], v[48:63]
	v_mfma_f32_32x32x16_bf16 v[32:47], v[92:95], v[108:111], v[32:47]
	s_cmp_eq_u32 s1, 64
	s_cbranch_scc1 .Lat_nowr
	s_cmp_eq_u32 s4, 1
	s_cselect_b32 s4, 0x5800, 0
	v_add3_u32 v214, s4, v225, v226
	v_add3_u32 v215, s4, v227, v228
	v_add3_u32 v216, s4, v229, v230
	v_add3_u32 v217, s4, v231, v200
	v_add3_u32 v196, s4, v232, v200
	s_waitcnt vmcnt(4)
	ds_write_b128 v214, v[176:179]
	s_waitcnt vmcnt(3)
	ds_write_b128 v215, v[180:183]
	s_waitcnt vmcnt(2)
	ds_write_b128 v216, v[184:187]
	s_waitcnt vmcnt(1)
	ds_write_b128 v217, v[188:191] offset:13312
	s_waitcnt vmcnt(0)
	ds_write_b128 v196, v[192:195] offset:13312
.Lat_nowr:
	s_add_i32 s1, s1, 1
	s_add_u32 s98, s98, s54
	s_addc_u32 s99, s99, s55
	s_add_u32 s100, s100, s76
	s_addc_u32 s101, s101, s77
	s_cmpk_eq_i32 s1, 0x41
	s_waitcnt lgkmcnt(0)
	s_barrier
	s_cbranch_scc0 .Lat_loop
	s_nop 7
	s_nop 7
	s_branch .LBB0_343
	.p2align 6
	s_nop 0
	s_nop 0
	s_nop 0
	s_nop 0
